# speedup vs baseline: 1.0085x; 1.0017x over previous
; template <bool FOX, int G>
; __device__ __forceinline__ void p3_attn(const Ptrs<G>& w, int seq, int h, int qb, bfu* sm, int kslot) {
;     ...
;     bool done;
;     if (FOX) {
;       const float fe = Fh[kt * 64 + 63];
;       done = (qb_[0] - fe - mrun[0] < -110.f) && (qb_[1] - fe - mrun[1] < -110.f);
;     } else {
;       done = (Rrun[0] < -110.f) && (Rrun[1] < -110.f);
;     }
;     {
;       const bool wd = (__builtin_amdgcn_ballot_w64(done) == ~0ull);
;       if (lane == 0) vote[wave] = wd ? 1 : 0;
;       __syncthreads();
;       if ((vote[0] & vote[1] & vote[2] & vote[3]) != 0) break;
;     }
; #pragma unroll
;     for (int q = 0; q < 2; ++q) {
;       *(bf16x8*)(Ks + (lrow + 32 * q) * 72 + lch) = rk[q];
;       *(bf16x8*)(Vs + (lrow + 32 * q) * 72 + lch) = rv[q];
;     }
;     __syncthreads();
.LBB0_319:
	s_or_b64 exec, exec, s[20:21]
	v_xor_b32_e32 v138, 0x8000, v138
	v_xor_b32_e32 v139, 0x8000, v139
	v_xor_b32_e32 v168, 0x8000, v168
	s_add_i32 s28, s28, -1
	s_sub_i32 s12, s12, 64
	s_cmp_eq_u32 s28, 0
	s_cselect_b64 s[0:1], -1, 0
	s_orn2_b64 s[0:1], s[0:1], exec

; template <bool FOX, int G>
; __device__ __forceinline__ void p3_attn(const Ptrs<G>& w, int seq, int h, int qb, bfu* sm, int kslot) {
;     ...
;     {
;       const bool wd = (__builtin_amdgcn_ballot_w64(done) == ~0ull);
;       if (lane == 0) vote[wave] = wd ? 1 : 0;
;       __syncthreads();
;       if ((vote[0] & vote[1] & vote[2] & vote[3]) != 0) break;
;     }
; #pragma unroll
;     for (int q = 0; q < 2; ++q) {
;       *(bf16x8*)(Ks + (lrow + 32 * q) * 72 + lch) = rk[q];
;       *(bf16x8*)(Vs + (lrow + 32 * q) * 72 + lch) = rv[q];
;     }
;     __syncthreads();
;     if (kt > 0) {
;       const int s1 = (kt - 1) * 64;
; #pragma unroll
;       for (int q = 0; q < 2; ++q) {
;         rk[q] = *(const bf16x8*)(qk + (rowbase + s1 + lrow + 32 * q) * 1024 + 512 + h * 64 + lch);
;         rv[q] = *(const bf16x8*)(Vt + (size_t)(lrow + 32 * q) * TSEQ + s1 + lch);
;       }
;     }
.LBB0_323:
	s_or_b64 exec, exec, s[0:1]
	ds_write_b128 v138, v[36:39]
	ds_write_b128 v138, v[40:43] offset:9216
	ds_write_b128 v138, v[44:47] offset:4608
	ds_write_b128 v138, v[32:35] offset:13824
	s_mov_b64 s[0:1], src_shared_base
	v_mov_b32_e32 v157, s1
	v_mov_b32_e32 v159, s1
	s_waitcnt lgkmcnt(0)
	s_barrier
	flat_load_dword v64, v[156:157] sc0 sc1
	s_waitcnt vmcnt(0)
	flat_load_dword v65, v[158:159] sc0 sc1
	s_waitcnt vmcnt(0)
	v_mov_b32_e32 v161, s1
	v_mov_b32_e32 v163, s1
	s_mov_b64 s[0:1], -1
	s_waitcnt lgkmcnt(0)
	v_and_b32_e32 v64, v65, v64
	flat_load_dword v65, v[160:161] sc0 sc1
	s_waitcnt vmcnt(0)
	flat_load_dword v66, v[162:163] sc0 sc1
	s_waitcnt vmcnt(0) lgkmcnt(0)
	v_bitop3_b32 v64, v64, v66, v65 bitop3:0x80
	v_cmp_eq_u32_e32 vcc, 0, v64
	s_and_saveexec_b64 s[18:19], vcc
	s_cbranch_execz .LBB0_320
	s_cmp_eq_u32 s28, 1
	s_cbranch_scc1 .LBB0_326
	s_mov_b32 s13, s3
	v_lshl_add_u64 v[32:33], v[134:135], 0, s[12:13]
	v_lshlrev_b64 v[32:33], 11, v[32:33]
	v_lshl_add_u64 v[32:33], s[64:65], 0, v[32:33]
	s_lshl_b32 s0, s27, 1
	s_mov_b32 s1, s3
	v_lshl_add_u64 v[34:35], s[12:13], 1, v[136:137]
	v_lshl_add_u64 v[32:33], v[32:33], 0, s[0:1]
	v_lshl_add_u64 v[32:33], v[32:33], 0, v[152:153]
	v_lshl_add_u64 v[40:41], v[34:35], 0, v[124:125]
	global_load_dwordx4 v[36:39], v[32:33], off offset:1024
	s_nop 0
	global_load_dwordx4 v[40:43], v[40:41], off
	v_add_co_u32_e32 v32, vcc, 0x10000, v32
	v_lshl_add_u64 v[34:35], v[34:35], 0, v[126:127]
	s_nop 0
	v_addc_co_u32_e32 v33, vcc, 0, v33, vcc
	global_load_dwordx4 v[44:47], v[32:33], off offset:1024
	s_nop 0
	global_load_dwordx4 v[32:35], v[34:35], off
